# LRU staging: 8 always-in-range rec row loads made unconditional with incremental addresses (drop per-load exec guard and v_mul_lo)
# speedup vs baseline: 1.0205x; 1.0019x over previous
; __global__ __launch_bounds__(512, 2) void mega(Params p) {
;     ...
;     const int total = 3 + p.nch * NSTEP;
;     for (int pc = 0; pc < total; ++pc) {
;         int z0; asm volatile("s_mov_b32 %0, 0" : "=s"(z0));
;         const int bid = blockIdx.x + z0, nblk = gridDim.x + z0;
;         int kind, arg, chunk;
;         if (pc < 3) { kind = pc == 0 ? K_PROLOGUE : K_GEMM; arg = 17 + pc; chunk = 0; }
;         else { const int q = pc - 3; chunk = q / NSTEP; const int s = q - chunk * NSTEP; kind = p.kind[s]; arg = p.arg[s]; }
.LBB0_13:
	s_or_b64 exec, exec, s[2:3]
	v_readlane_b32 s0, v254, 0
	v_readlane_b32 s1, v254, 1
	s_load_dword s0, s[0:1], 0x17c
	s_mov_b32 s79, 0
	s_barrier
	s_waitcnt lgkmcnt(0)
	s_cmp_lt_i32 s0, 0
	s_cbranch_scc1 .LBB0_663
	v_readlane_b32 s2, v254, 0
	v_readlane_b32 s3, v254, 1
	s_load_dwordx8 s[8:15], s[2:3], 0x150
	s_mul_i32 s0, s0, 27
	v_mbcnt_lo_u32_b32 v0, -1, 0
	v_mbcnt_hi_u32_b32 v213, -1, v0
	v_mov_b32_e32 v11, 0
	s_waitcnt lgkmcnt(0)
	s_cmp_lg_u64 s[12:13], 0
	s_cselect_b64 s[4:5], -1, 0
	s_add_i32 s74, s0, 2
	v_writelane_b32 v254, s4, 2
	s_max_i32 s88, s74, 0
	s_add_u32 s0, s12, 0x400
	v_writelane_b32 v254, s5, 3
	v_writelane_b32 v254, s0, 4
	s_addc_u32 s0, s13, 0
	v_writelane_b32 v254, s0, 5
	s_add_u32 s0, s8, 0xc00
	v_writelane_b32 v254, s0, 6
	s_addc_u32 s0, s9, 0
	v_writelane_b32 v254, s0, 7
	s_add_i32 s0, 0, 0x3808
	v_writelane_b32 v254, s0, 8
	s_add_i32 s4, 0, 0x21ff0
	v_writelane_b32 v254, s4, 9
	s_add_i32 s4, 0, 0x21ff4
	v_writelane_b32 v254, s4, 10
	s_load_dword s4, s[2:3], 0x178
	s_load_dwordx2 s[6:7], s[2:3], 0x170
	v_and_b32_e32 v0, 64, v213
	s_load_dwordx2 s[2:3], s[2:3], 0xd8
	v_mov_b32_e32 v212, 0x358637bd
	s_waitcnt lgkmcnt(0)
	v_writelane_b32 v254, s4, 11
	v_writelane_b32 v254, s6, 12
	s_mov_b32 s97, 0x800000
	s_movk_i32 s43, 0x1400
	v_writelane_b32 v254, s7, 13
	v_writelane_b32 v254, s2, 14
	s_mov_b32 s56, 0x66666667
	s_mov_b32 s57, 0x13e000
	v_writelane_b32 v254, s3, 15
	v_writelane_b32 v254, s75, 16
	v_writelane_b32 v254, s89, 17
	v_writelane_b32 v254, s8, 18
	s_movk_i32 s33, 0x1000
	s_mov_b32 s69, 0x13d000
	v_writelane_b32 v254, s9, 19
	v_writelane_b32 v254, s10, 20
	v_writelane_b32 v254, s11, 21
	v_writelane_b32 v254, s12, 22
	v_writelane_b32 v254, s13, 23
	v_writelane_b32 v254, s14, 24
	v_writelane_b32 v254, s15, 25
	v_writelane_b32 v254, s74, 26
	s_movk_i32 s76, 0x2000
	s_mov_b32 s36, 0x13c000
	s_movk_i32 s37, 0x3000
	s_mov_b32 s38, 0x13b000
	s_movk_i32 s39, 0x5000
	s_mov_b32 s54, 0x139000
	s_movk_i32 s55, 0x6000
	s_mov_b32 s60, 0x138000
	s_movk_i32 s78, 0x7000
	s_mov_b32 s90, 0x137000
	s_mov_b32 s0, 0x8000
	s_mov_b32 s91, 0x136000
	s_mov_b32 s73, 0xa000
	s_mov_b32 s34, 0xb000
	s_mov_b32 s96, 0x10000
	s_movk_i32 s42, 0x800
	s_movk_i32 s77, 0xa00
	s_movk_i32 s35, 0x110
	s_mov_b32 s1, 0xf800000
	v_mov_b32_e32 v214, 0x260
	s_movk_i32 s95, 0x7fff
	v_mov_b32_e32 v119, 0xbf1f24be
	v_mov_b32_e32 v120, 0x3e642e9d
	v_add_u32_e32 v219, 64, v0
	v_xor_b32_e32 v230, 32, v213
	v_xor_b32_e32 v215, 16, v213
	v_xor_b32_e32 v121, 8, v213
	v_xor_b32_e32 v122, 4, v213
	v_xor_b32_e32 v123, 2, v213
	v_xor_b32_e32 v126, 1, v213
	v_mov_b32_e32 v124, 0xffff8000
	v_mov_b32_e32 v218, 0x7fc00000
	v_mov_b32_e32 v125, 0xffc00000
	v_mov_b32_e32 v158, 0x3f317218
	v_mov_b32_e32 v229, 0xfffff000
	v_mov_b32_e32 v228, 0x5800
	v_mov_b32_e32 v231, 0x41b17218
	v_mov_b32_e32 v232, 0xa0
	s_mov_b32 s5, 0
	s_mov_b64 s[50:51], 0xa00
	s_mov_b64 s[100:101], 0x1400
	s_mov_b64 s[92:93], 0x80
	s_mov_b32 s94, 0x3dd2d3e8
	v_writelane_b32 v254, s88, 27
	s_branch .LBB0_16

; __device__ void lru_fused_phase(const int bid, const int nblk, bf16_t* __restrict__ U, bf16_t* __restrict__ HF, const bf16_t* __restrict__ Wg, const float* __restrict__ cw, const float* __restrict__ cb, ...
;     ...
;                     const int kn = e == 0 ? kk + 1 : 30 - kk; const int p0 = 64 * kn + 8 * wid - 2;
; #pragma unroll
;                     for (int i = 0; i < 11; ++i) { const int pos = p0 + i; xr[i] = (pos >= 0 && pos < SEQ) ? *(const unsigned*)(recp + (long)pos * (2 * DRNN)) : 0u; }
;                 }
.LBB0_98:
	s_or_b64 exec, exec, s[8:9]
	v_add_u32_e32 v10, s10, v9
	v_mul_lo_u32 v10, v10, s77
	v_lshl_add_u64 v[38:39], v[10:11], 1, v[60:61]
	global_load_dword v89, v[38:39], off offset:2560
	v_lshl_add_u64 v[38:39], v[38:39], 0, s[100:101]
	global_load_dword v90, v[38:39], off offset:2560
	v_lshl_add_u64 v[38:39], v[38:39], 0, s[100:101]
	global_load_dword v92, v[38:39], off offset:2560
	v_lshl_add_u64 v[38:39], v[38:39], 0, s[100:101]
	global_load_dword v93, v[38:39], off offset:2560
	v_lshl_add_u64 v[38:39], v[38:39], 0, s[100:101]
	global_load_dword v94, v[38:39], off offset:2560
	v_lshl_add_u64 v[38:39], v[38:39], 0, s[100:101]
	global_load_dword v95, v[38:39], off offset:2560
	v_lshl_add_u64 v[38:39], v[38:39], 0, s[100:101]
	global_load_dword v96, v[38:39], off offset:2560
	v_lshl_add_u64 v[38:39], v[38:39], 0, s[100:101]
	global_load_dword v97, v[38:39], off offset:2560
	s_mov_b64 s[8:9], exec

; __global__ __launch_bounds__(512, 2) void mega(Params p) {
	.amdhsa_kernel _Z4mega6Params
		.amdhsa_group_segment_fixed_size 0
		.amdhsa_private_segment_fixed_size 0
		.amdhsa_kernarg_size 3584
		.amdhsa_user_sgpr_count 2
		.amdhsa_user_sgpr_dispatch_ptr 0
		.amdhsa_user_sgpr_queue_ptr 0
		.amdhsa_user_sgpr_kernarg_segment_ptr 1
		.amdhsa_user_sgpr_dispatch_id 0
		.amdhsa_user_sgpr_kernarg_preload_length 0
		.amdhsa_user_sgpr_kernarg_preload_offset 0
		.amdhsa_user_sgpr_private_segment_size 0
		.amdhsa_uses_dynamic_stack 0
		.amdhsa_enable_private_segment 0
		.amdhsa_system_sgpr_workgroup_id_x 1
		.amdhsa_system_sgpr_workgroup_id_y 0
		.amdhsa_system_sgpr_workgroup_id_z 0
		.amdhsa_system_sgpr_workgroup_info 0
		.amdhsa_system_vgpr_workitem_id 2
		.amdhsa_next_free_vgpr 256
		.amdhsa_next_free_sgpr 102
		.amdhsa_accum_offset 256
		.amdhsa_reserve_vcc 1
		.amdhsa_float_round_mode_32 0
		.amdhsa_float_round_mode_16_64 0
		.amdhsa_float_denorm_mode_32 3
		.amdhsa_float_denorm_mode_16_64 3
		.amdhsa_dx10_clamp 1
		.amdhsa_ieee_mode 1
		.amdhsa_fp16_overflow 0
		.amdhsa_tg_split 0
		.amdhsa_exception_fp_ieee_invalid_op 0
		.amdhsa_exception_fp_denorm_src 0
		.amdhsa_exception_fp_ieee_div_zero 0
		.amdhsa_exception_fp_ieee_overflow 0
		.amdhsa_exception_fp_ieee_underflow 0
		.amdhsa_exception_fp_ieee_inexact 0
		.amdhsa_exception_int_div_zero 0
	.end_amdhsa_kernel

; __global__ __launch_bounds__(512, 2) void mega(Params p) {
amdhsa.kernels:
  - .agpr_count:     0
    .args:
      - .offset:         0
        .size:           3328
        .value_kind:     by_value
      - .offset:         3328
        .size:           4
        .value_kind:     hidden_block_count_x
      - .offset:         3332
        .size:           4
        .value_kind:     hidden_block_count_y
      - .offset:         3336
        .size:           4
        .value_kind:     hidden_block_count_z
      - .offset:         3340
        .size:           2
        .value_kind:     hidden_group_size_x
      - .offset:         3342
        .size:           2
        .value_kind:     hidden_group_size_y
      - .offset:         3344
        .size:           2
        .value_kind:     hidden_group_size_z
      - .offset:         3346
        .size:           2
        .value_kind:     hidden_remainder_x
      - .offset:         3348
        .size:           2
        .value_kind:     hidden_remainder_y
      - .offset:         3350
        .size:           2
        .value_kind:     hidden_remainder_z
      - .offset:         3368
        .size:           8
        .value_kind:     hidden_global_offset_x
      - .offset:         3376
        .size:           8
        .value_kind:     hidden_global_offset_y
      - .offset:         3384
        .size:           8
        .value_kind:     hidden_global_offset_z
      - .offset:         3392
        .size:           2
        .value_kind:     hidden_grid_dims
      - .offset:         3416
        .size:           8
        .value_kind:     hidden_multigrid_sync_arg
      - .offset:         3448
        .size:           4
        .value_kind:     hidden_dynamic_lds_size
    .group_segment_fixed_size: 0
    .kernarg_segment_align: 8
    .kernarg_segment_size: 3584
    .language:       OpenCL C
    .language_version:
      - 2
      - 0
    .max_flat_workgroup_size: 512
    .name:           _Z4mega6Params
    .private_segment_fixed_size: 0
    .sgpr_count:     108
    .sgpr_spill_count: 113
    .symbol:         _Z4mega6Params.kd
    .uniform_work_group_size: 1
    .uses_dynamic_stack: false
    .vgpr_count:     256
    .vgpr_spill_count: 0
    .wavefront_size: 64
